# MLP-in epilogue: H stores carry sc1 nt (streaming) instead of sc1; rest identical to v34
# speedup vs baseline: 1.0033x; 1.0033x over previous
; __device__ __forceinline__ unsigned cvt_pk_bf16(float lo, float hi) { f32x2 v = {lo, hi}; bf16x2_t b = __builtin_convertvector(v, bf16x2_t); return __builtin_bit_cast(unsigned, b); }
;     __device__ __forceinline__ void operator()(const f32x4 (&acc)[2][2][4][2], const Unit& u, int wr, int wc, int fr, int fq) const {
;     ...
;                 if (MODE == 0 || MODE == 1) {
; #pragma unroll
;                     for (int bj = 0; bj < 2; ++bj) {
;                         const int hf = 2 * u.pn + bj;
;                         bf16_t* dst;
;                         if (split2) dst = ((hf & 1) ? O2 : O) + (size_t)row * ldc + (hf >> 1) * 128 + wc * 32 + 8 * fq;
;                         else dst = O + (size_t)row * ldc + hf * 128 + wc * 32 + 8 * fq;
;                         f32x4 v0 = acc[ai][bj][m][0] * sc, v1 = acc[ai][bj][m][1] * sc;
;                         if (MODE == 1) {
; #pragma unroll
;                             for (int e = 0; e < 4; ++e) { float a = fmaxf(v0[e], 0.f), b = fmaxf(v1[e], 0.f); v0[e] = a * a; v1[e] = b * b; }
;                         }
;                         u32x4 w; w.x = cvt_pk_bf16(v0[0], v0[1]); w.y = cvt_pk_bf16(v0[2], v0[3]); w.z = cvt_pk_bf16(v1[0], v1[1]); w.w = cvt_pk_bf16(v1[2], v1[3]);
;                         if (MODE == 1) asm volatile("global_store_dwordx4 %0, %1, off sc1\n\ts_nop 1" :: "v"(dst), "v"(w) : "memory");
;                         else *(u32x4*)dst = w;
;                     }
.LBB0_1070:
	v_lshl_add_u32 v142, s46, 8, v144
	s_lshl_b32 s6, s44, 8
	v_ashrrev_i32_e32 v143, 31, v142
	v_max_f32_e32 v120, 0, v120
	v_max_f32_e32 v121, 0, v121
	v_lshlrev_b64 v[140:141], 13, v[142:143]
	s_ashr_i32 s7, s6, 31
	v_pk_mul_f32 v[148:149], v[120:121], v[120:121]
	v_lshl_add_u64 v[140:141], s[88:89], 0, v[140:141]
	s_lshl_b64 s[6:7], s[6:7], 1
	v_max_f32_e32 v122, 0, v122
	v_max_f32_e32 v123, 0, v123
	v_lshl_add_u64 v[140:141], v[140:141], 0, s[6:7]
	v_max_f32_e32 v124, 0, v124
	v_max_f32_e32 v125, 0, v125
	v_max_f32_e32 v120, 0, v126
	v_max_f32_e32 v121, 0, v127
	v_pk_mul_f32 v[150:151], v[122:123], v[122:123]
	v_lshl_add_u64 v[140:141], v[140:141], 0, s[50:51]
	v_pk_mul_f32 v[124:125], v[124:125], v[124:125]
	v_pk_mul_f32 v[126:127], v[120:121], v[120:121]
	v_cvt_pk_bf16_f32 v122, v148, v149
	v_cvt_pk_bf16_f32 v123, v150, v151
	v_max_f32_e32 v112, 0, v112
	v_max_f32_e32 v113, 0, v113
	v_lshl_add_u64 v[140:141], v[140:141], 0, v[180:181]
	v_cvt_pk_bf16_f32 v120, v124, v125
	v_cvt_pk_bf16_f32 v121, v126, v127
	global_store_dwordx4 v[140:141], v[120:123], off sc1 nt
	s_nop 1
	v_pk_mul_f32 v[122:123], v[112:113], v[112:113]
	v_max_f32_e32 v116, 0, v116
	v_max_f32_e32 v117, 0, v117
	v_max_f32_e32 v114, 0, v114
	v_pk_mul_f32 v[116:117], v[116:117], v[116:117]
	v_max_f32_e32 v112, 0, v118
	v_max_f32_e32 v113, 0, v119
	v_max_f32_e32 v115, 0, v115
	s_mov_b64 s[26:27], 0x100
	v_pk_mul_f32 v[118:119], v[112:113], v[112:113]
	v_pk_mul_f32 v[124:125], v[114:115], v[114:115]
	v_cvt_pk_bf16_f32 v112, v116, v117
	v_lshl_add_u64 v[120:121], v[140:141], 0, s[26:27]
	v_cvt_pk_bf16_f32 v113, v118, v119
	v_cvt_pk_bf16_f32 v114, v122, v123
	v_cvt_pk_bf16_f32 v115, v124, v125
	global_store_dwordx4 v[120:121], v[112:115], off sc1 nt
	s_nop 1
	v_or_b32_e32 v112, 16, v142
	v_ashrrev_i32_e32 v113, 31, v112
	v_max_f32_e32 v104, 0, v104
	v_max_f32_e32 v105, 0, v105
	v_lshlrev_b64 v[112:113], 13, v[112:113]
	v_pk_mul_f32 v[114:115], v[104:105], v[104:105]
	v_lshl_add_u64 v[112:113], s[88:89], 0, v[112:113]
	v_max_f32_e32 v106, 0, v106
	v_max_f32_e32 v107, 0, v107
	v_lshl_add_u64 v[112:113], v[112:113], 0, s[6:7]
	v_max_f32_e32 v108, 0, v108
	v_max_f32_e32 v109, 0, v109
	v_max_f32_e32 v104, 0, v110
	v_max_f32_e32 v105, 0, v111
	v_pk_mul_f32 v[116:117], v[106:107], v[106:107]
	v_lshl_add_u64 v[112:113], v[112:113], 0, s[50:51]
	v_pk_mul_f32 v[108:109], v[108:109], v[108:109]
	v_pk_mul_f32 v[110:111], v[104:105], v[104:105]
	v_cvt_pk_bf16_f32 v106, v114, v115
	v_cvt_pk_bf16_f32 v107, v116, v117
	v_max_f32_e32 v96, 0, v96
	v_max_f32_e32 v97, 0, v97
	v_lshl_add_u64 v[112:113], v[112:113], 0, v[180:181]
	v_cvt_pk_bf16_f32 v104, v108, v109
	v_cvt_pk_bf16_f32 v105, v110, v111
	global_store_dwordx4 v[112:113], v[104:107], off sc1 nt
	s_nop 1
	v_pk_mul_f32 v[106:107], v[96:97], v[96:97]
	v_max_f32_e32 v100, 0, v100
	v_max_f32_e32 v101, 0, v101
	v_max_f32_e32 v98, 0, v98
	v_pk_mul_f32 v[100:101], v[100:101], v[100:101]
	v_max_f32_e32 v96, 0, v102
	v_max_f32_e32 v97, 0, v103
	v_max_f32_e32 v99, 0, v99
	v_pk_mul_f32 v[102:103], v[96:97], v[96:97]
	v_pk_mul_f32 v[108:109], v[98:99], v[98:99]
	v_cvt_pk_bf16_f32 v96, v100, v101
	v_lshl_add_u64 v[104:105], v[112:113], 0, s[26:27]
	v_cvt_pk_bf16_f32 v97, v102, v103
	v_cvt_pk_bf16_f32 v98, v106, v107
	v_cvt_pk_bf16_f32 v99, v108, v109
	global_store_dwordx4 v[104:105], v[96:99], off sc1 nt
	s_nop 1
	v_or_b32_e32 v96, 32, v142
	v_ashrrev_i32_e32 v97, 31, v96
	v_max_f32_e32 v88, 0, v88
	v_max_f32_e32 v89, 0, v89
	v_lshlrev_b64 v[96:97], 13, v[96:97]
	v_pk_mul_f32 v[98:99], v[88:89], v[88:89]
	v_lshl_add_u64 v[96:97], s[88:89], 0, v[96:97]
	v_max_f32_e32 v90, 0, v90
	v_max_f32_e32 v91, 0, v91
	v_lshl_add_u64 v[96:97], v[96:97], 0, s[6:7]
	v_max_f32_e32 v92, 0, v92
	v_max_f32_e32 v93, 0, v93
	v_max_f32_e32 v88, 0, v94
	v_max_f32_e32 v89, 0, v95
	v_pk_mul_f32 v[100:101], v[90:91], v[90:91]
	v_lshl_add_u64 v[96:97], v[96:97], 0, s[50:51]
	v_pk_mul_f32 v[92:93], v[92:93], v[92:93]
	v_pk_mul_f32 v[94:95], v[88:89], v[88:89]
	v_cvt_pk_bf16_f32 v90, v98, v99
	v_cvt_pk_bf16_f32 v91, v100, v101
	v_max_f32_e32 v80, 0, v80
	v_max_f32_e32 v81, 0, v81
	v_lshl_add_u64 v[96:97], v[96:97], 0, v[180:181]
	v_cvt_pk_bf16_f32 v88, v92, v93
	v_cvt_pk_bf16_f32 v89, v94, v95
	global_store_dwordx4 v[96:97], v[88:91], off sc1 nt
	s_nop 1
	v_pk_mul_f32 v[90:91], v[80:81], v[80:81]
	v_max_f32_e32 v84, 0, v84
	v_max_f32_e32 v85, 0, v85
	v_max_f32_e32 v82, 0, v82
	v_pk_mul_f32 v[84:85], v[84:85], v[84:85]
	v_max_f32_e32 v80, 0, v86
	v_max_f32_e32 v81, 0, v87
	v_max_f32_e32 v83, 0, v83
	v_pk_mul_f32 v[86:87], v[80:81], v[80:81]
	v_pk_mul_f32 v[92:93], v[82:83], v[82:83]
	v_cvt_pk_bf16_f32 v80, v84, v85
	v_lshl_add_u64 v[88:89], v[96:97], 0, s[26:27]
	v_cvt_pk_bf16_f32 v81, v86, v87
	v_cvt_pk_bf16_f32 v82, v90, v91
	v_cvt_pk_bf16_f32 v83, v92, v93
	global_store_dwordx4 v[88:89], v[80:83], off sc1 nt
	s_nop 1
	v_or_b32_e32 v80, 48, v142
	v_ashrrev_i32_e32 v81, 31, v80
	v_max_f32_e32 v72, 0, v72
	v_max_f32_e32 v73, 0, v73
	v_lshlrev_b64 v[80:81], 13, v[80:81]
	v_pk_mul_f32 v[82:83], v[72:73], v[72:73]
	v_lshl_add_u64 v[80:81], s[88:89], 0, v[80:81]
	v_max_f32_e32 v74, 0, v74
	v_max_f32_e32 v75, 0, v75
	v_lshl_add_u64 v[80:81], v[80:81], 0, s[6:7]
	v_max_f32_e32 v76, 0, v76
	v_max_f32_e32 v77, 0, v77
	v_max_f32_e32 v72, 0, v78
	v_max_f32_e32 v73, 0, v79
	v_pk_mul_f32 v[84:85], v[74:75], v[74:75]
	v_lshl_add_u64 v[80:81], v[80:81], 0, s[50:51]
	v_pk_mul_f32 v[76:77], v[76:77], v[76:77]
	v_pk_mul_f32 v[78:79], v[72:73], v[72:73]
	v_cvt_pk_bf16_f32 v74, v82, v83
	v_cvt_pk_bf16_f32 v75, v84, v85
	v_max_f32_e32 v64, 0, v64
	v_max_f32_e32 v65, 0, v65
; __device__ __forceinline__ unsigned cvt_pk_bf16(float lo, float hi) { f32x2 v = {lo, hi}; bf16x2_t b = __builtin_convertvector(v, bf16x2_t); return __builtin_bit_cast(unsigned, b); }
;     __device__ __forceinline__ void operator()(const f32x4 (&acc)[2][2][4][2], const Unit& u, int wr, int wc, int fr, int fq) const {
;     ...
;                 if (MODE == 0 || MODE == 1) {
; #pragma unroll
;                     for (int bj = 0; bj < 2; ++bj) {
;                         const int hf = 2 * u.pn + bj;
;                         bf16_t* dst;
;                         if (split2) dst = ((hf & 1) ? O2 : O) + (size_t)row * ldc + (hf >> 1) * 128 + wc * 32 + 8 * fq;
;                         else dst = O + (size_t)row * ldc + hf * 128 + wc * 32 + 8 * fq;
;                         f32x4 v0 = acc[ai][bj][m][0] * sc, v1 = acc[ai][bj][m][1] * sc;
;                         if (MODE == 1) {
; #pragma unroll
;                             for (int e = 0; e < 4; ++e) { float a = fmaxf(v0[e], 0.f), b = fmaxf(v1[e], 0.f); v0[e] = a * a; v1[e] = b * b; }
;                         }
;                         u32x4 w; w.x = cvt_pk_bf16(v0[0], v0[1]); w.y = cvt_pk_bf16(v0[2], v0[3]); w.z = cvt_pk_bf16(v1[0], v1[1]); w.w = cvt_pk_bf16(v1[2], v1[3]);
;                         if (MODE == 1) asm volatile("global_store_dwordx4 %0, %1, off sc1\n\ts_nop 1" :: "v"(dst), "v"(w) : "memory");
;                         else *(u32x4*)dst = w;
;                     }
	v_lshl_add_u64 v[80:81], v[80:81], 0, v[180:181]
	v_cvt_pk_bf16_f32 v72, v76, v77
	v_cvt_pk_bf16_f32 v73, v78, v79
	global_store_dwordx4 v[80:81], v[72:75], off sc1 nt
	s_nop 1
	v_pk_mul_f32 v[74:75], v[64:65], v[64:65]
	v_max_f32_e32 v66, 0, v66
	v_max_f32_e32 v67, 0, v67
	v_max_f32_e32 v68, 0, v68
	v_max_f32_e32 v69, 0, v69
	v_max_f32_e32 v64, 0, v70
	v_max_f32_e32 v65, 0, v71
	v_pk_mul_f32 v[76:77], v[66:67], v[66:67]
	v_pk_mul_f32 v[68:69], v[68:69], v[68:69]
	v_pk_mul_f32 v[70:71], v[64:65], v[64:65]
	v_cvt_pk_bf16_f32 v66, v74, v75
	v_cvt_pk_bf16_f32 v67, v76, v77
	v_max_f32_e32 v56, 0, v56
	v_max_f32_e32 v57, 0, v57
	v_lshl_add_u64 v[72:73], v[80:81], 0, s[26:27]
	v_cvt_pk_bf16_f32 v64, v68, v69
	v_cvt_pk_bf16_f32 v65, v70, v71
	global_store_dwordx4 v[72:73], v[64:67], off sc1 nt
	s_nop 1
	v_pk_mul_f32 v[66:67], v[56:57], v[56:57]
	v_max_f32_e32 v58, 0, v58
	v_max_f32_e32 v59, 0, v59
	v_max_f32_e32 v60, 0, v60
	v_max_f32_e32 v61, 0, v61
	v_max_f32_e32 v56, 0, v62
	v_max_f32_e32 v57, 0, v63
	v_pk_mul_f32 v[68:69], v[58:59], v[58:59]
	s_mov_b64 s[6:7], 0x100000
	v_pk_mul_f32 v[60:61], v[60:61], v[60:61]
	v_pk_mul_f32 v[62:63], v[56:57], v[56:57]
	v_cvt_pk_bf16_f32 v58, v66, v67
	v_cvt_pk_bf16_f32 v59, v68, v69
	v_max_f32_e32 v48, 0, v48
	v_max_f32_e32 v49, 0, v49
	v_lshl_add_u64 v[64:65], v[140:141], 0, s[6:7]
	v_cvt_pk_bf16_f32 v56, v60, v61
	v_cvt_pk_bf16_f32 v57, v62, v63
	global_store_dwordx4 v[64:65], v[56:59], off sc1 nt
	s_nop 1
	v_pk_mul_f32 v[58:59], v[48:49], v[48:49]
	v_max_f32_e32 v50, 0, v50
	v_max_f32_e32 v51, 0, v51
	v_max_f32_e32 v52, 0, v52
	v_max_f32_e32 v53, 0, v53
	v_max_f32_e32 v48, 0, v54
	v_max_f32_e32 v49, 0, v55
	v_pk_mul_f32 v[60:61], v[50:51], v[50:51]
	s_mov_b64 s[6:7], 0x100100
	v_pk_mul_f32 v[52:53], v[52:53], v[52:53]
	v_pk_mul_f32 v[54:55], v[48:49], v[48:49]
	v_cvt_pk_bf16_f32 v50, v58, v59
	v_cvt_pk_bf16_f32 v51, v60, v61
	v_max_f32_e32 v40, 0, v40
	v_max_f32_e32 v41, 0, v41
	v_lshl_add_u64 v[56:57], v[140:141], 0, s[6:7]
	v_cvt_pk_bf16_f32 v48, v52, v53
	v_cvt_pk_bf16_f32 v49, v54, v55
	global_store_dwordx4 v[56:57], v[48:51], off sc1 nt
	s_nop 1
	v_pk_mul_f32 v[50:51], v[40:41], v[40:41]
	v_max_f32_e32 v42, 0, v42
	v_max_f32_e32 v43, 0, v43
	v_max_f32_e32 v44, 0, v44
	v_max_f32_e32 v45, 0, v45
	v_max_f32_e32 v40, 0, v46
	v_max_f32_e32 v41, 0, v47
	v_pk_mul_f32 v[52:53], v[42:43], v[42:43]
	s_mov_b64 s[6:7], 0x120000
	v_pk_mul_f32 v[44:45], v[44:45], v[44:45]
	v_pk_mul_f32 v[46:47], v[40:41], v[40:41]
	v_cvt_pk_bf16_f32 v42, v50, v51
	v_cvt_pk_bf16_f32 v43, v52, v53
	v_max_f32_e32 v32, 0, v32
	v_max_f32_e32 v33, 0, v33
	v_lshl_add_u64 v[48:49], v[140:141], 0, s[6:7]
	v_cvt_pk_bf16_f32 v40, v44, v45
	v_cvt_pk_bf16_f32 v41, v46, v47
	global_store_dwordx4 v[48:49], v[40:43], off sc1 nt
	s_nop 1
	v_pk_mul_f32 v[42:43], v[32:33], v[32:33]
	v_max_f32_e32 v34, 0, v34
	v_max_f32_e32 v35, 0, v35
	v_max_f32_e32 v36, 0, v36
	v_max_f32_e32 v37, 0, v37
	v_max_f32_e32 v32, 0, v38
	v_max_f32_e32 v33, 0, v39
	v_pk_mul_f32 v[44:45], v[34:35], v[34:35]
	s_mov_b64 s[6:7], 0x120100
	v_pk_mul_f32 v[36:37], v[36:37], v[36:37]
	v_pk_mul_f32 v[38:39], v[32:33], v[32:33]
	v_cvt_pk_bf16_f32 v34, v42, v43
	v_cvt_pk_bf16_f32 v35, v44, v45
	v_max_f32_e32 v24, 0, v24
	v_max_f32_e32 v25, 0, v25
	v_lshl_add_u64 v[40:41], v[140:141], 0, s[6:7]
	v_cvt_pk_bf16_f32 v32, v36, v37
	v_cvt_pk_bf16_f32 v33, v38, v39
	global_store_dwordx4 v[40:41], v[32:35], off sc1 nt
	s_nop 1
	v_pk_mul_f32 v[34:35], v[24:25], v[24:25]
	v_max_f32_e32 v26, 0, v26
	v_max_f32_e32 v27, 0, v27
	v_max_f32_e32 v28, 0, v28
	v_max_f32_e32 v29, 0, v29
	v_max_f32_e32 v24, 0, v30
	v_max_f32_e32 v25, 0, v31
	v_pk_mul_f32 v[36:37], v[26:27], v[26:27]
	s_mov_b64 s[6:7], 0x140000
	v_pk_mul_f32 v[28:29], v[28:29], v[28:29]
	v_pk_mul_f32 v[30:31], v[24:25], v[24:25]
	v_cvt_pk_bf16_f32 v26, v34, v35
	v_cvt_pk_bf16_f32 v27, v36, v37
	v_max_f32_e32 v16, 0, v16
	v_max_f32_e32 v17, 0, v17
	v_lshl_add_u64 v[32:33], v[140:141], 0, s[6:7]
	v_cvt_pk_bf16_f32 v24, v28, v29
	v_cvt_pk_bf16_f32 v25, v30, v31
	global_store_dwordx4 v[32:33], v[24:27], off sc1 nt
	s_nop 1
	v_pk_mul_f32 v[26:27], v[16:17], v[16:17]
	v_max_f32_e32 v18, 0, v18
	v_max_f32_e32 v19, 0, v19
	v_max_f32_e32 v20, 0, v20
	v_max_f32_e32 v21, 0, v21
	v_max_f32_e32 v16, 0, v22
	v_max_f32_e32 v17, 0, v23
	v_pk_mul_f32 v[28:29], v[18:19], v[18:19]
	s_mov_b64 s[6:7], 0x140100
	v_pk_mul_f32 v[20:21], v[20:21], v[20:21]
	v_pk_mul_f32 v[22:23], v[16:17], v[16:17]
	v_cvt_pk_bf16_f32 v18, v26, v27
	v_cvt_pk_bf16_f32 v19, v28, v29
	v_max_f32_e32 v8, 0, v8
	v_max_f32_e32 v9, 0, v9
	v_lshl_add_u64 v[24:25], v[140:141], 0, s[6:7]
	v_cvt_pk_bf16_f32 v16, v20, v21
	v_cvt_pk_bf16_f32 v17, v22, v23
	global_store_dwordx4 v[24:25], v[16:19], off sc1 nt
	s_nop 1
	v_pk_mul_f32 v[18:19], v[8:9], v[8:9]
	v_max_f32_e32 v10, 0, v10
	v_max_f32_e32 v11, 0, v11
	v_max_f32_e32 v12, 0, v12
	v_max_f32_e32 v13, 0, v13
	v_max_f32_e32 v8, 0, v14
	v_max_f32_e32 v9, 0, v15
	v_pk_mul_f32 v[20:21], v[10:11], v[10:11]
	s_mov_b64 s[6:7], 0x160000
	v_pk_mul_f32 v[12:13], v[12:13], v[12:13]
	v_pk_mul_f32 v[14:15], v[8:9], v[8:9]
	v_cvt_pk_bf16_f32 v10, v18, v19
	v_cvt_pk_bf16_f32 v11, v20, v21
	v_max_f32_e32 v0, 0, v0
	v_max_f32_e32 v1, 0, v1
	v_lshl_add_u64 v[16:17], v[140:141], 0, s[6:7]
	v_cvt_pk_bf16_f32 v8, v12, v13
	v_cvt_pk_bf16_f32 v9, v14, v15
	global_store_dwordx4 v[16:17], v[8:11], off sc1 nt
	s_nop 1
	v_pk_mul_f32 v[10:11], v[0:1], v[0:1]
	v_max_f32_e32 v2, 0, v2
	v_max_f32_e32 v4, 0, v4
	v_max_f32_e32 v5, 0, v5
	v_max_f32_e32 v0, 0, v6
	v_max_f32_e32 v1, 0, v7
	v_max_f32_e32 v3, 0, v3
	s_mov_b64 s[6:7], 0x160100
	v_pk_mul_f32 v[4:5], v[4:5], v[4:5]
	v_pk_mul_f32 v[6:7], v[0:1], v[0:1]
	v_pk_mul_f32 v[12:13], v[2:3], v[2:3]
	v_lshl_add_u64 v[8:9], v[140:141], 0, s[6:7]
	v_cvt_pk_bf16_f32 v0, v4, v5
	v_cvt_pk_bf16_f32 v1, v6, v7
	v_cvt_pk_bf16_f32 v2, v10, v11
	v_cvt_pk_bf16_f32 v3, v12, v13
	global_store_dwordx4 v[8:9], v[0:3], off sc1 nt
	s_nop 1
	s_andn2_b64 vcc, exec, s[38:39]
	s_mov_b64 s[6:7], -1
	s_cbranch_vccnz .LBB0_1058
	s_andn2_b64 vcc, exec, s[0:1]
	s_cbranch_vccnz .LBB0_1057
	s_barrier
	s_branch .LBB0_1057
